# NSA top-k threshold search: two queries per step with four independent compare masks so VALU-to-SALU latency is paid once per pair
# baseline (speedup 1.0000x reference)
; __device__ __forceinline__ void nsa_attn_phase(const bf16* P, const bf16* VT, const bf16* kcmp, const bf16* vcmpT, bf16* O, unsigned* ctr, lds_u8* lds, int G, int bid, int tid) {
;     ...
; #pragma unroll 1
;     ...
; #pragma unroll
;                     for (int k = 0; k < 8; ++k) { const int cand = thr[k] | (1 << bit);
;                         const int c = __builtin_popcountll(__ballot(v0[k] >= cand)) + __builtin_popcountll(__ballot(v1[k] >= cand));
;                         thr[k] = c >= 13 ? cand : thr[k]; }
;                 }
; #pragma unroll
;                 for (int k = 0; k < 8; ++k) { const int q = wave * 8 + i4 + k;
;                     const bool gt0 = v0[k] > thr[k], gt1 = v1[k] > thr[k], eq0 = v0[k] == thr[k], eq1 = v1[k] == thr[k];
;                     const int need = 13 - (__builtin_popcountll(__ballot(gt0)) + __builtin_popcountll(__ballot(gt1)));
;                     const unsigned long long be0 = __ballot(eq0), be1 = __ballot(eq1), lm = (1ull << lane) - 1ull;
;                     const int re0 = __builtin_popcountll(be0 & lm), re1 = __builtin_popcountll(be0) + __builtin_popcountll(be1 & lm);
;                     const bool sel0 = gt0 || (eq0 && re0 < need) || s0i == 0 || s0i == qb || s0i == qb - 1;
.LBB0_491:
	s_lshl_b32 s1, 1, s0
	s_waitcnt lgkmcnt(0)
	s_or_b32 s18, s1, s26
	s_or_b32 s39, s1, s38
	v_cmp_le_i32_e32 vcc, s18, v15
	v_cmp_le_i32_e64 s[16:17], s18, v16
	v_cmp_le_i32_e64 s[24:25], s39, v13
	v_cmp_le_i32_e64 s[34:35], s39, v14
	s_bcnt1_i32_b64 s16, s[16:17]
	s_bcnt1_i32_b64 s17, vcc
	s_add_i32 s16, s16, s17
	s_cmp_gt_u32 s16, 12
	s_cselect_b32 s26, s18, s26
	s_bcnt1_i32_b64 s24, s[24:25]
	s_bcnt1_i32_b64 s25, s[34:35]
	s_add_i32 s24, s24, s25
	s_cmp_gt_u32 s24, 12
	s_cselect_b32 s38, s39, s38
	s_or_b32 s18, s1, s57
	s_or_b32 s39, s1, s56
	v_cmp_le_i32_e32 vcc, s18, v11
	v_cmp_le_i32_e64 s[16:17], s18, v12
	v_cmp_le_i32_e64 s[24:25], s39, v9
	v_cmp_le_i32_e64 s[34:35], s39, v10
	s_bcnt1_i32_b64 s16, s[16:17]
	s_bcnt1_i32_b64 s17, vcc
	s_add_i32 s16, s16, s17
	s_cmp_gt_u32 s16, 12
	s_cselect_b32 s57, s18, s57
	s_bcnt1_i32_b64 s24, s[24:25]
	s_bcnt1_i32_b64 s25, s[34:35]
	s_add_i32 s24, s24, s25
	s_cmp_gt_u32 s24, 12
	s_cselect_b32 s56, s39, s56
	s_or_b32 s18, s1, s55
	s_or_b32 s39, s1, s54
	v_cmp_le_i32_e32 vcc, s18, v7
	v_cmp_le_i32_e64 s[16:17], s18, v8
	v_cmp_le_i32_e64 s[24:25], s39, v5
	v_cmp_le_i32_e64 s[34:35], s39, v6
	s_bcnt1_i32_b64 s16, s[16:17]
	s_bcnt1_i32_b64 s17, vcc
	s_add_i32 s16, s16, s17
	s_cmp_gt_u32 s16, 12
	s_cselect_b32 s55, s18, s55
	s_bcnt1_i32_b64 s24, s[24:25]
	s_bcnt1_i32_b64 s25, s[34:35]
	s_add_i32 s24, s24, s25
	s_cmp_gt_u32 s24, 12
	s_cselect_b32 s54, s39, s54
	s_or_b32 s18, s1, s52
	s_or_b32 s39, s1, s33
	v_cmp_le_i32_e32 vcc, s18, v2
	v_cmp_le_i32_e64 s[16:17], s18, v4
	v_cmp_le_i32_e64 s[24:25], s39, v0
	v_cmp_le_i32_e64 s[34:35], s39, v1
	s_bcnt1_i32_b64 s16, s[16:17]
	s_bcnt1_i32_b64 s17, vcc
	s_add_i32 s16, s16, s17
	s_cmp_gt_u32 s16, 12
	s_cselect_b32 s52, s18, s52
	s_bcnt1_i32_b64 s24, s[24:25]
	s_bcnt1_i32_b64 s25, s[34:35]
	s_add_i32 s24, s24, s25
	s_cmp_gt_u32 s24, 12
	s_cselect_b32 s33, s39, s33
	s_add_i32 s0, s0, -1
	s_cmp_eq_u32 s0, -1
	s_cbranch_scc0 .LBB0_491
	v_cmp_lt_i32_e64 s[0:1], s26, v16
	v_cmp_lt_i32_e64 s[24:25], s26, v15
	s_bcnt1_i32_b64 s24, s[24:25]
	s_bcnt1_i32_b64 s25, s[0:1]
	v_cmp_eq_u32_e64 s[16:17], s48, v139
	s_sub_i32 s39, 0x7e, s49
	s_add_i32 s24, s24, s25
	s_nor_b64 s[34:35], s[8:9], s[16:17]
	v_cmp_eq_u32_e32 vcc, s39, v139
	v_cmp_ge_i32_e64 s[20:21], s26, v15
	v_cmp_ne_u32_e64 s[18:19], s26, v15
	v_cmp_eq_u32_e64 s[22:23], s26, v16
	s_sub_i32 s40, 13, s24
	v_cmp_eq_u32_e64 s[24:25], s26, v15
	s_mov_b64 s[30:31], -1
	s_and_saveexec_b64 s[26:27], s[20:21]
	s_cbranch_execz .LBB0_498
	s_mov_b64 s[20:21], 0
	s_and_saveexec_b64 s[30:31], s[18:19]
	s_xor_b64 s[18:19], exec, s[30:31]
	s_cbranch_execnz .LBB0_616
	s_andn2_saveexec_b64 s[30:31], s[18:19]
	s_cbranch_execnz .LBB0_617
